# attention loop: softmax max/scale/exp moved under PV MFMAs in both halves
# speedup vs baseline: 1.0037x; 1.0037x over previous
.LBB0_535:
	ds_read_b128 v[64:67], v208 offset:49152
	ds_read_b128 v[68:71], v208 offset:57344
	ds_read_b128 v[196:199], v213 offset:49152
	ds_read_b128 v[200:203], v213 offset:57344
	v_add_f32_e32 v162, 0, v163
	v_add_f32_e32 v162, v177, v162
	s_waitcnt lgkmcnt(3)
	v_mfma_f32_32x32x16_bf16 v[80:95], v[64:67], v[118:121], 0
	v_add_f32_e32 v162, v164, v162
	v_add_f32_e32 v162, v184, v162
	v_add_f32_e32 v162, v176, v162
	v_add_f32_e32 v162, v185, v162
	v_add_f32_e32 v162, v165, v162
	v_add_f32_e32 v162, v175, v162
	v_add_f32_e32 v162, v166, v162
	s_waitcnt lgkmcnt(2)
	v_mfma_f32_32x32x16_bf16 v[64:79], v[68:71], v[118:121], 0
	v_add_f32_e32 v162, v173, v162
	v_add_f32_e32 v162, v167, v162
	v_add_f32_e32 v162, v174, v162
	v_exp_f32_e32 v160, v160
	v_add_f32_e32 v162, v168, v162
	v_exp_f32_e32 v161, v161
	v_add_f32_e32 v162, v171, v162
	s_waitcnt lgkmcnt(1)
	v_mfma_f32_32x32x16_bf16 v[80:95], v[196:199], v[114:117], v[80:95]
	v_exp_f32_e32 v158, v158
	v_add_f32_e32 v162, v169, v162
	v_exp_f32_e32 v159, v159
	v_add_f32_e32 v162, v172, v162
	v_exp_f32_e32 v154, v154
	v_add_f32_e32 v162, v160, v162
	v_exp_f32_e32 v155, v155
	s_waitcnt lgkmcnt(0)
	v_mfma_f32_32x32x16_bf16 v[64:79], v[200:203], v[114:117], v[64:79]
	ds_read_b128 v[196:199], v212 offset:49152
	ds_read_b128 v[200:203], v212 offset:57344
	v_add_f32_e32 v162, v161, v162
	v_exp_f32_e32 v150, v150
	v_add_f32_e32 v162, v158, v162
	v_exp_f32_e32 v151, v151
	v_add_f32_e32 v162, v159, v162
	v_exp_f32_e32 v148, v148
	s_waitcnt lgkmcnt(1)
	v_mfma_f32_32x32x16_bf16 v[80:95], v[196:199], v[126:129], v[80:95]
	v_add_f32_e32 v162, v154, v162
	v_exp_f32_e32 v149, v149
	v_add_f32_e32 v162, v155, v162
	v_exp_f32_e32 v156, v156
	v_add_f32_e32 v162, v150, v162
	v_exp_f32_e32 v157, v157
	v_add_f32_e32 v162, v151, v162
	s_waitcnt lgkmcnt(0)
	v_mfma_f32_32x32x16_bf16 v[64:79], v[200:203], v[126:129], v[64:79]
	ds_read_b128 v[196:199], v211 offset:49152
	ds_read_b128 v[200:203], v211 offset:57344
	v_exp_f32_e32 v152, v152
	v_add_f32_e32 v162, v148, v162
	v_exp_f32_e32 v153, v153
	v_add_f32_e32 v162, v149, v162
	v_exp_f32_e32 v146, v146
	v_add_f32_e32 v162, v156, v162
	s_waitcnt lgkmcnt(1)
	v_mfma_f32_32x32x16_bf16 v[80:95], v[196:199], v[122:125], v[80:95]
	v_exp_f32_e32 v147, v147
	v_add_f32_e32 v162, v157, v162
	v_add_f32_e32 v162, v152, v162
	v_add_f32_e32 v162, v153, v162
	v_add_f32_e32 v162, v146, v162
	v_add_f32_e32 v217, v147, v162
	v_mov_b32_e32 v218, v217
	s_waitcnt lgkmcnt(0)
	v_mfma_f32_32x32x16_bf16 v[64:79], v[200:203], v[122:125], v[64:79]
	ds_read_b128 v[196:199], v210 offset:49152
	ds_read_b128 v[200:203], v210 offset:57344
	v_permlane32_swap_b32_e32 v217, v218
	s_waitcnt lgkmcnt(1)
	v_mfma_f32_32x32x16_bf16 v[80:95], v[196:199], v[110:113], v[80:95]
	s_waitcnt lgkmcnt(0)
	v_mfma_f32_32x32x16_bf16 v[64:79], v[200:203], v[110:113], v[64:79]
	ds_read_b128 v[196:199], v209 offset:49152
	ds_read_b128 v[200:203], v209 offset:57344
	s_waitcnt lgkmcnt(1)
	v_mfma_f32_32x32x16_bf16 v[80:95], v[196:199], v[106:109], v[80:95]
	s_waitcnt lgkmcnt(0)
	v_mfma_f32_32x32x16_bf16 v[64:79], v[200:203], v[106:109], v[64:79]
	ds_read_b128 v[196:199], v215 offset:49152
	ds_read_b128 v[200:203], v215 offset:57344
	s_waitcnt lgkmcnt(1)
	v_mfma_f32_32x32x16_bf16 v[80:95], v[196:199], v[102:105], v[80:95]
	s_waitcnt lgkmcnt(0)
	v_mfma_f32_32x32x16_bf16 v[64:79], v[200:203], v[102:105], v[64:79]
	ds_read_b128 v[196:199], v214 offset:49152
	ds_read_b128 v[200:203], v214 offset:57344
	v_cvt_pk_bf16_f32 v162, v163, v177
	v_cvt_pk_bf16_f32 v163, v164, v184
	v_cvt_pk_bf16_f32 v164, v176, v185
	v_cvt_pk_bf16_f32 v165, v165, v175
	v_cvt_pk_bf16_f32 v166, v166, v173
	v_cvt_pk_bf16_f32 v167, v167, v174
	s_waitcnt lgkmcnt(1)
	v_mfma_f32_32x32x16_bf16 v[80:95], v[196:199], v[98:101], v[80:95]
	v_permlane32_swap_b32_e32 v162, v164
	v_cvt_pk_bf16_f32 v168, v168, v171
	v_cvt_pk_bf16_f32 v169, v169, v172
	v_cvt_pk_bf16_f32 v172, v160, v161
	v_cvt_pk_bf16_f32 v173, v158, v159
	v_cvt_pk_bf16_f32 v174, v154, v155
	s_waitcnt lgkmcnt(0)
	v_mfma_f32_32x32x16_bf16 v[64:79], v[200:203], v[98:101], v[64:79]
	v_cvt_pk_bf16_f32 v175, v150, v151
	v_cvt_pk_bf16_f32 v196, v148, v149
	v_cvt_pk_bf16_f32 v197, v156, v157
	v_cvt_pk_bf16_f32 v198, v152, v153
	v_cvt_pk_bf16_f32 v199, v146, v147
	v_permlane32_swap_b32_e32 v163, v165
	v_permlane32_swap_b32_e32 v166, v168
	v_permlane32_swap_b32_e32 v167, v169
	v_permlane32_swap_b32_e32 v172, v174
	v_permlane32_swap_b32_e32 v173, v175
	v_permlane32_swap_b32_e32 v196, v198
	v_permlane32_swap_b32_e32 v197, v199
	v_lshl_add_u64 v[186:187], v[180:181], 0, v[96:97]
	s_mov_b32 s8, 0x1edc0000
	v_add_co_u32_e32 v146, vcc, s8, v186
	s_mov_b32 s8, 0x1ede0000
	s_nop 0
	v_addc_co_u32_e32 v147, vcc, 0, v187, vcc
	v_add_co_u32_e32 v150, vcc, s8, v186
	v_lshl_add_u64 v[184:185], v[182:183], 0, v[96:97]
	s_nop 0
	v_addc_co_u32_e32 v151, vcc, 0, v187, vcc
	s_mov_b32 s8, 0x1bbc0000
	v_add_co_u32_e32 v154, vcc, s8, v184
	s_mov_b32 s8, 0x1bbe0000
	s_nop 0
	v_addc_co_u32_e32 v155, vcc, 0, v185, vcc
	v_add_co_u32_e32 v158, vcc, s8, v184
	global_load_dwordx4 v[146:149], v[146:147], off
	s_nop 0
	global_load_dwordx4 v[150:153], v[150:151], off
	v_addc_co_u32_e32 v159, vcc, 0, v185, vcc
	global_load_dwordx4 v[154:157], v[154:155], off
	s_nop 0
	global_load_dwordx4 v[158:161], v[158:159], off
	ds_read_b64_tr_b16 v[200:201], v193 offset:0
	ds_read_b64_tr_b16 v[202:203], v193 offset:0x800
	ds_read_b64_tr_b16 v[220:221], v193 offset:0x1000
	ds_read_b64_tr_b16 v[222:223], v193 offset:0x1800
	ds_read_b64_tr_b16 v[224:225], v193 offset:0x2000
	ds_read_b64_tr_b16 v[226:227], v193 offset:0x2800
	ds_read_b64_tr_b16 v[234:235], v193 offset:0x3000
	ds_read_b64_tr_b16 v[236:237], v193 offset:0x3800
	s_waitcnt lgkmcnt(0)
	s_nop 0
	v_mfma_f32_32x32x16_bf16 v[0:15], v[162:165], v[200:203], v[0:15]
	ds_read_b64_tr_b16 v[200:201], v193 offset:0x200
	ds_read_b64_tr_b16 v[202:203], v193 offset:0xa00
	v_max_f32_e32 v230, v81, v81
	v_max_f32_e32 v231, v80, v80
	v_max_f32_e32 v230, v231, v230
	v_max3_f32 v230, v230, v82, v83
	v_max3_f32 v230, v230, v84, v85
	v_mfma_f32_32x32x16_bf16 v[0:15], v[166:169], v[220:223], v[0:15]
	ds_read_b64_tr_b16 v[220:221], v193 offset:0x1200
	ds_read_b64_tr_b16 v[222:223], v193 offset:0x1a00
	v_max3_f32 v230, v230, v86, v87
	v_max3_f32 v230, v230, v88, v89
	v_max3_f32 v230, v230, v90, v91
	v_max3_f32 v230, v230, v92, v93
	v_max3_f32 v230, v230, v94, v95
	v_mfma_f32_32x32x16_bf16 v[0:15], v[172:175], v[224:227], v[0:15]
	ds_read_b64_tr_b16 v[224:225], v193 offset:0x2200
	ds_read_b64_tr_b16 v[226:227], v193 offset:0x2a00
	v_max3_f32 v230, v230, v64, v65
	v_max3_f32 v230, v230, v66, v67
	v_max3_f32 v230, v230, v68, v69
	v_max3_f32 v230, v230, v70, v71
	v_mfma_f32_32x32x16_bf16 v[0:15], v[196:199], v[234:237], v[0:15]
	ds_read_b64_tr_b16 v[234:235], v193 offset:0x3200
	ds_read_b64_tr_b16 v[236:237], v193 offset:0x3a00
	v_max3_f32 v230, v230, v72, v73
	v_max3_f32 v230, v230, v74, v75
	v_max3_f32 v230, v230, v76, v77
	v_max3_f32 v230, v230, v78, v79
	s_waitcnt lgkmcnt(0)
	v_mfma_f32_32x32x16_bf16 v[48:63], v[162:165], v[200:203], v[48:63]
	ds_read_b64_tr_b16 v[200:201], v193 offset:0x400
	ds_read_b64_tr_b16 v[202:203], v193 offset:0xc00
	v_mov_b32_e32 v231, v230
	s_nop 1
	v_permlane32_swap_b32_e32 v230, v231
	v_max_f32_e32 v231, v231, v231
	v_max_f32_e32 v230, v230, v230
	v_max_f32_e32 v230, v230, v231
	v_mfma_f32_32x32x16_bf16 v[48:63], v[166:169], v[220:223], v[48:63]
	ds_read_b64_tr_b16 v[220:221], v193 offset:0x1400
	ds_read_b64_tr_b16 v[222:223], v193 offset:0x1c00
	v_sub_f32_e32 v231, v230, v170
	v_cmp_ge_f32_e32 vcc, s33, v231
	v_max_f32_e32 v231, v170, v170
	v_max_f32_e32 v230, v231, v230
	v_sub_f32_e32 v231, v170, v230
	v_mul_f32_e32 v231, 0x3e0293ee, v231
	v_exp_f32_e32 v231, v231
	v_mfma_f32_32x32x16_bf16 v[48:63], v[172:175], v[224:227], v[48:63]
	ds_read_b64_tr_b16 v[224:225], v193 offset:0x2400
	ds_read_b64_tr_b16 v[226:227], v193 offset:0x2c00
	s_cmp_eq_u64 vcc, exec
	s_cselect_b64 s[8:9], -1, 0
	v_cndmask_b32_e64 v219, v231, 1.0, s[8:9]
	v_cndmask_b32_e64 v232, v230, v170, s[8:9]
	v_mul_f32_e32 v240, 0xbe0293ee, v232
	v_mfma_f32_32x32x16_bf16 v[48:63], v[196:199], v[234:237], v[48:63]
	ds_read_b64_tr_b16 v[234:235], v193 offset:0x3400
	ds_read_b64_tr_b16 v[236:237], v193 offset:0x3c00
	v_fmamk_f32 v80, v80, 0x3e0293ee, v240
	v_fmamk_f32 v81, v81, 0x3e0293ee, v240
	v_fmamk_f32 v82, v82, 0x3e0293ee, v240
	v_fmamk_f32 v83, v83, 0x3e0293ee, v240
	s_waitcnt lgkmcnt(0)
	v_mfma_f32_32x32x16_bf16 v[32:47], v[162:165], v[200:203], v[32:47]
	ds_read_b64_tr_b16 v[200:201], v193 offset:0x600
	ds_read_b64_tr_b16 v[202:203], v193 offset:0xe00
	v_fmamk_f32 v84, v84, 0x3e0293ee, v240
	v_fmamk_f32 v85, v85, 0x3e0293ee, v240
	v_fmamk_f32 v86, v86, 0x3e0293ee, v240
	v_fmamk_f32 v87, v87, 0x3e0293ee, v240
	v_fmamk_f32 v88, v88, 0x3e0293ee, v240
	v_fmamk_f32 v89, v89, 0x3e0293ee, v240
	v_mfma_f32_32x32x16_bf16 v[32:47], v[166:169], v[220:223], v[32:47]
	ds_read_b64_tr_b16 v[220:221], v193 offset:0x1600
	ds_read_b64_tr_b16 v[222:223], v193 offset:0x1e00
	v_fmamk_f32 v90, v90, 0x3e0293ee, v240
	v_fmamk_f32 v91, v91, 0x3e0293ee, v240
	v_fmamk_f32 v92, v92, 0x3e0293ee, v240
	v_fmamk_f32 v93, v93, 0x3e0293ee, v240
	v_fmamk_f32 v94, v94, 0x3e0293ee, v240
	v_fmamk_f32 v95, v95, 0x3e0293ee, v240
	v_mfma_f32_32x32x16_bf16 v[32:47], v[172:175], v[224:227], v[32:47]
	ds_read_b64_tr_b16 v[224:225], v193 offset:0x2600
	ds_read_b64_tr_b16 v[226:227], v193 offset:0x2e00
	v_exp_f32_e32 v177, v81
	v_exp_f32_e32 v176, v83
	v_mfma_f32_32x32x16_bf16 v[32:47], v[196:199], v[234:237], v[32:47]
	ds_read_b64_tr_b16 v[234:235], v193 offset:0x3600
	ds_read_b64_tr_b16 v[236:237], v193 offset:0x3e00
	v_exp_f32_e32 v171, v93
	v_exp_f32_e32 v170, v95
	s_waitcnt lgkmcnt(0)
	v_mfma_f32_32x32x16_bf16 v[16:31], v[162:165], v[200:203], v[16:31]
	v_exp_f32_e32 v162, v80
	v_exp_f32_e32 v163, v82
	v_exp_f32_e32 v164, v84
	v_exp_f32_e32 v165, v86
	v_mfma_f32_32x32x16_bf16 v[16:31], v[166:169], v[220:223], v[16:31]
	v_exp_f32_e32 v166, v88
	v_exp_f32_e32 v167, v90
	v_exp_f32_e32 v168, v92
	v_exp_f32_e32 v169, v94
	v_mfma_f32_32x32x16_bf16 v[16:31], v[172:175], v[224:227], v[16:31]
	v_exp_f32_e32 v175, v85
	v_exp_f32_e32 v174, v87
	v_exp_f32_e32 v173, v89
	v_exp_f32_e32 v172, v91
	v_mfma_f32_32x32x16_bf16 v[16:31], v[196:199], v[234:237], v[16:31]
	s_barrier
	s_waitcnt vmcnt(4)
	v_cmp_gt_f32_e32 vcc, 1.0, v219
	s_waitcnt vmcnt(4)
	ds_write_b128 v205, v[130:133]
	ds_write_b128 v206, v[134:137]
	ds_write_b128 v204, v[138:141] offset:32768
	ds_write_b128 v207, v[142:145] offset:32768
	s_cbranch_vccz .LBB0_539
	s_and_saveexec_b64 s[10:11], s[6:7]
	ds_write_b32 v190, v219 offset:128
	s_or_b64 exec, exec, s[10:11]
	s_waitcnt lgkmcnt(0)
	ds_read_b128 v[240:243], v179 offset:224
	ds_read_b128 v[244:247], v179 offset:192
	ds_read_b128 v[196:199], v179 offset:160
	ds_read_b128 v[200:203], v179 offset:128
	s_waitcnt lgkmcnt(3)
	v_pk_mul_f32 v[14:15], v[14:15], v[242:243]
	s_waitcnt lgkmcnt(2)
	v_pk_mul_f32 v[10:11], v[10:11], v[246:247]
	s_waitcnt lgkmcnt(1)
	v_pk_mul_f32 v[6:7], v[6:7], v[198:199]
	s_waitcnt lgkmcnt(0)
	v_pk_mul_f32 v[2:3], v[2:3], v[202:203]
	v_pk_mul_f32 v[12:13], v[12:13], v[240:241]
	v_pk_mul_f32 v[8:9], v[8:9], v[244:245]
	v_pk_mul_f32 v[4:5], v[4:5], v[196:197]
	v_pk_mul_f32 v[0:1], v[0:1], v[200:201]
	v_pk_mul_f32 v[62:63], v[62:63], v[242:243]
	v_pk_mul_f32 v[58:59], v[58:59], v[246:247]
	v_pk_mul_f32 v[54:55], v[54:55], v[198:199]
	v_pk_mul_f32 v[50:51], v[50:51], v[202:203]
	v_pk_mul_f32 v[60:61], v[60:61], v[240:241]
	v_pk_mul_f32 v[56:57], v[56:57], v[244:245]
	v_pk_mul_f32 v[52:53], v[52:53], v[196:197]
	v_pk_mul_f32 v[48:49], v[48:49], v[200:201]
	v_pk_mul_f32 v[46:47], v[46:47], v[242:243]
	v_pk_mul_f32 v[42:43], v[42:43], v[246:247]
	v_pk_mul_f32 v[38:39], v[38:39], v[198:199]
	v_pk_mul_f32 v[34:35], v[34:35], v[202:203]
	v_pk_mul_f32 v[44:45], v[44:45], v[240:241]
	v_pk_mul_f32 v[40:41], v[40:41], v[244:245]
	v_pk_mul_f32 v[36:37], v[36:37], v[196:197]
	v_pk_mul_f32 v[32:33], v[32:33], v[200:201]
	v_pk_mul_f32 v[30:31], v[30:31], v[242:243]
	v_pk_mul_f32 v[26:27], v[26:27], v[246:247]
	v_pk_mul_f32 v[22:23], v[22:23], v[198:199]
	v_pk_mul_f32 v[18:19], v[18:19], v[202:203]
	v_pk_mul_f32 v[28:29], v[28:29], v[240:241]
	v_pk_mul_f32 v[24:25], v[24:25], v[244:245]
	v_pk_mul_f32 v[20:21], v[20:21], v[196:197]
	v_pk_mul_f32 v[16:17], v[16:17], v[200:201]
.LBB0_539:
	v_mov_b32_e32 v220, v232
	v_mul_f32_e32 v221, 0xbe0293ee, v220
	v_fmamk_f32 v233, v64, 0x3e0293ee, v221
	v_fmamk_f32 v234, v65, 0x3e0293ee, v221
	v_fmamk_f32 v235, v66, 0x3e0293ee, v221
	v_fmamk_f32 v236, v67, 0x3e0293ee, v221
	v_fmamk_f32 v237, v68, 0x3e0293ee, v221
	v_fmamk_f32 v223, v69, 0x3e0293ee, v221
	v_fmamk_f32 v224, v70, 0x3e0293ee, v221
	v_fmamk_f32 v225, v71, 0x3e0293ee, v221
	v_fmamk_f32 v226, v72, 0x3e0293ee, v221
	v_fmamk_f32 v227, v73, 0x3e0293ee, v221
	v_fmamk_f32 v228, v74, 0x3e0293ee, v221
	v_fmamk_f32 v229, v75, 0x3e0293ee, v221
	v_fmamk_f32 v222, v76, 0x3e0293ee, v221
	v_fmamk_f32 v238, v77, 0x3e0293ee, v221
	v_fmamk_f32 v239, v78, 0x3e0293ee, v221
	v_fmac_f32_e32 v221, 0x3e0293ee, v79
	s_waitcnt lgkmcnt(0)
	s_barrier
	ds_read_b128 v[64:67], v208 offset:32768
	ds_read_b128 v[68:71], v208 offset:40960
	ds_read_b128 v[196:199], v213 offset:32768
	ds_read_b128 v[200:203], v213 offset:40960
	v_exp_f32_e32 v195, v233
	s_waitcnt lgkmcnt(3)
	v_mfma_f32_32x32x16_bf16 v[80:95], v[64:67], v[118:121], 0
	s_waitcnt lgkmcnt(2)
	v_mfma_f32_32x32x16_bf16 v[64:79], v[68:71], v[118:121], 0
	s_waitcnt lgkmcnt(0)
	v_mfma_f32_32x32x16_bf16 v[64:79], v[200:203], v[114:117], v[64:79]
	v_mfma_f32_32x32x16_bf16 v[80:95], v[196:199], v[114:117], v[80:95]
	ds_read_b128 v[196:199], v212 offset:32768
	ds_read_b128 v[200:203], v212 offset:40960
	s_waitcnt lgkmcnt(0)
	v_mfma_f32_32x32x16_bf16 v[64:79], v[200:203], v[126:129], v[64:79]
	v_mfma_f32_32x32x16_bf16 v[80:95], v[196:199], v[126:129], v[80:95]
	ds_read_b128 v[196:199], v211 offset:32768
	ds_read_b128 v[200:203], v211 offset:40960
	s_waitcnt lgkmcnt(0)
	v_mfma_f32_32x32x16_bf16 v[64:79], v[200:203], v[122:125], v[64:79]
	v_mfma_f32_32x32x16_bf16 v[80:95], v[196:199], v[122:125], v[80:95]
	ds_read_b128 v[196:199], v210 offset:32768
	ds_read_b128 v[200:203], v210 offset:40960
	s_waitcnt lgkmcnt(0)
	v_mfma_f32_32x32x16_bf16 v[64:79], v[200:203], v[110:113], v[64:79]
	v_mfma_f32_32x32x16_bf16 v[80:95], v[196:199], v[110:113], v[80:95]
	ds_read_b128 v[196:199], v209 offset:32768
	ds_read_b128 v[200:203], v209 offset:40960
	s_waitcnt lgkmcnt(0)
	v_mfma_f32_32x32x16_bf16 v[64:79], v[200:203], v[106:109], v[64:79]
	v_mfma_f32_32x32x16_bf16 v[80:95], v[196:199], v[106:109], v[80:95]
	ds_read_b128 v[196:199], v215 offset:32768
	ds_read_b128 v[200:203], v215 offset:40960
	s_waitcnt lgkmcnt(0)
	v_mfma_f32_32x32x16_bf16 v[64:79], v[200:203], v[102:105], v[64:79]
	v_mfma_f32_32x32x16_bf16 v[80:95], v[196:199], v[102:105], v[80:95]
	ds_read_b128 v[196:199], v214 offset:32768
	ds_read_b128 v[200:203], v214 offset:40960
	s_waitcnt lgkmcnt(0)
	v_mfma_f32_32x32x16_bf16 v[64:79], v[200:203], v[98:101], v[64:79]
	v_exp_f32_e32 v202, v225
	v_exp_f32_e32 v225, v229
	v_exp_f32_e32 v229, v221
	v_add_f32_e32 v221, 0, v162
	v_add_f32_e32 v221, v177, v221
	v_add_f32_e32 v221, v163, v221
	v_add_f32_e32 v221, v176, v221
	v_add_f32_e32 v221, v164, v221
	v_add_f32_e32 v221, v175, v221
	v_add_f32_e32 v221, v165, v221
	v_add_f32_e32 v221, v174, v221
	v_add_f32_e32 v221, v166, v221
	v_add_f32_e32 v221, v173, v221
	v_add_f32_e32 v221, v167, v221
	v_add_f32_e32 v221, v172, v221
	v_add_f32_e32 v221, v168, v221
	v_mfma_f32_32x32x16_bf16 v[80:95], v[196:199], v[98:101], v[80:95]
	v_exp_f32_e32 v196, v234
	v_add_f32_e32 v221, v171, v221
	v_exp_f32_e32 v197, v235
	v_add_f32_e32 v221, v169, v221
	v_exp_f32_e32 v198, v236
	v_add_f32_e32 v221, v170, v221
	v_exp_f32_e32 v199, v237
	v_add_f32_e32 v221, v195, v221
	v_exp_f32_e32 v200, v223
	v_add_f32_e32 v221, v196, v221
	v_exp_f32_e32 v201, v224
	v_add_f32_e32 v221, v197, v221
	v_add_f32_e32 v221, v198, v221
	v_exp_f32_e32 v203, v226
	v_add_f32_e32 v221, v199, v221
	v_exp_f32_e32 v223, v227
	v_add_f32_e32 v221, v200, v221
	v_exp_f32_e32 v224, v228
	v_add_f32_e32 v221, v201, v221
	v_add_f32_e32 v221, v202, v221
	v_exp_f32_e32 v226, v222
	v_add_f32_e32 v221, v203, v221
	v_exp_f32_e32 v227, v238
	v_add_f32_e32 v221, v223, v221
	v_exp_f32_e32 v228, v239
	v_add_f32_e32 v221, v224, v221
	v_add_f32_e32 v221, v225, v221
	v_add_f32_e32 v221, v226, v221
	v_add_f32_e32 v221, v227, v221
	v_add_f32_e32 v221, v228, v221
	v_add_f32_e32 v221, v229, v221
	v_mov_b32_e32 v222, v221
	v_cvt_pk_bf16_f32 v162, v162, v177
	v_cvt_pk_bf16_f32 v163, v163, v176
	v_cvt_pk_bf16_f32 v164, v164, v175
	v_cvt_pk_bf16_f32 v165, v165, v174
	v_cvt_pk_bf16_f32 v166, v166, v173
	v_cvt_pk_bf16_f32 v167, v167, v172
	v_cvt_pk_bf16_f32 v168, v168, v171
	v_cvt_pk_bf16_f32 v169, v169, v170
	v_cvt_pk_bf16_f32 v170, v195, v196
	v_cvt_pk_bf16_f32 v171, v197, v198
	v_cvt_pk_bf16_f32 v172, v199, v200
	v_cvt_pk_bf16_f32 v173, v201, v202
	v_cvt_pk_bf16_f32 v174, v203, v223
	v_cvt_pk_bf16_f32 v175, v224, v225
	v_cvt_pk_bf16_f32 v176, v226, v227
	v_cvt_pk_bf16_f32 v177, v228, v229
	s_nop 1
	v_permlane32_swap_b32_e32 v221, v222
	v_permlane32_swap_b32_e32 v162, v164
	v_permlane32_swap_b32_e32 v163, v165
	v_permlane32_swap_b32_e32 v166, v168
	v_permlane32_swap_b32_e32 v167, v169
	v_permlane32_swap_b32_e32 v170, v172
	v_permlane32_swap_b32_e32 v171, v173
	v_permlane32_swap_b32_e32 v174, v176
	v_permlane32_swap_b32_e32 v175, v177
	s_cmp_ge_u32 s30, s31
	s_cselect_b64 s[10:11], -1, 0
	s_and_b64 vcc, exec, s[10:11]
	s_cbranch_vccnz .LBB0_541
	v_add_co_u32_e32 v130, vcc, 0x1ee00000, v186
	s_nop 1
	v_addc_co_u32_e32 v131, vcc, 0, v187, vcc
	v_add_co_u32_e32 v134, vcc, 0x1ee20000, v186
	s_nop 1
	v_addc_co_u32_e32 v135, vcc, 0, v187, vcc
	v_add_co_u32_e32 v138, vcc, 0x1bc00000, v184
	global_load_dwordx4 v[130:133], v[130:131], off
	s_nop 0
	global_load_dwordx4 v[134:137], v[134:135], off
	v_addc_co_u32_e32 v139, vcc, 0, v185, vcc
	v_add_co_u32_e32 v142, vcc, 0x1bc20000, v184
	s_nop 1
	v_addc_co_u32_e32 v143, vcc, 0, v185, vcc
	global_load_dwordx4 v[138:141], v[138:139], off
	s_nop 0
	global_load_dwordx4 v[142:145], v[142:143], off
.LBB0_541:
	ds_read_b64_tr_b16 v[184:185], v191 offset:0
	ds_read_b64_tr_b16 v[186:187], v191 offset:0x800
	ds_read_b64_tr_b16 v[196:197], v191 offset:0x1000
	ds_read_b64_tr_b16 v[198:199], v191 offset:0x1800
	ds_read_b64_tr_b16 v[200:201], v191 offset:0x2000
	ds_read_b64_tr_b16 v[202:203], v191 offset:0x2800
	ds_read_b64_tr_b16 v[224:225], v191 offset:0x3000
	ds_read_b64_tr_b16 v[226:227], v191 offset:0x3800
	s_waitcnt lgkmcnt(0)
	s_nop 0
	v_mfma_f32_32x32x16_bf16 v[0:15], v[162:165], v[184:187], v[0:15]
	ds_read_b64_tr_b16 v[184:185], v191 offset:0x200
	ds_read_b64_tr_b16 v[186:187], v191 offset:0xa00
	v_max_f32_e32 v230, v81, v81
	v_max_f32_e32 v231, v80, v80
	v_max_f32_e32 v230, v231, v230
	v_max3_f32 v230, v230, v82, v83
	v_max3_f32 v230, v230, v84, v85
	v_mfma_f32_32x32x16_bf16 v[0:15], v[166:169], v[196:199], v[0:15]
	ds_read_b64_tr_b16 v[196:197], v191 offset:0x1200
	ds_read_b64_tr_b16 v[198:199], v191 offset:0x1a00
	v_max3_f32 v230, v230, v86, v87
	v_max3_f32 v230, v230, v88, v89
	v_max3_f32 v230, v230, v90, v91
	v_max3_f32 v230, v230, v92, v93
	v_max3_f32 v230, v230, v94, v95
	v_mfma_f32_32x32x16_bf16 v[0:15], v[170:173], v[200:203], v[0:15]
	ds_read_b64_tr_b16 v[200:201], v191 offset:0x2200
	ds_read_b64_tr_b16 v[202:203], v191 offset:0x2a00
	v_max3_f32 v230, v230, v64, v65
	v_max3_f32 v230, v230, v66, v67
	v_max3_f32 v230, v230, v68, v69
	v_max3_f32 v230, v230, v70, v71
	v_mfma_f32_32x32x16_bf16 v[0:15], v[174:177], v[224:227], v[0:15]
	ds_read_b64_tr_b16 v[224:225], v191 offset:0x3200
	ds_read_b64_tr_b16 v[226:227], v191 offset:0x3a00
	v_max3_f32 v230, v230, v72, v73
	v_max3_f32 v230, v230, v74, v75
	v_max3_f32 v230, v230, v76, v77
	v_max3_f32 v230, v230, v78, v79
	s_waitcnt lgkmcnt(0)
	v_mfma_f32_32x32x16_bf16 v[48:63], v[162:165], v[184:187], v[48:63]
	ds_read_b64_tr_b16 v[184:185], v191 offset:0x400
	ds_read_b64_tr_b16 v[186:187], v191 offset:0xc00
	v_mov_b32_e32 v231, v230
	s_nop 1
	v_permlane32_swap_b32_e32 v230, v231
	v_max_f32_e32 v231, v231, v231
	v_max_f32_e32 v230, v230, v230
	v_max_f32_e32 v230, v230, v231
	v_mfma_f32_32x32x16_bf16 v[48:63], v[166:169], v[196:199], v[48:63]
	ds_read_b64_tr_b16 v[196:197], v191 offset:0x1400
	ds_read_b64_tr_b16 v[198:199], v191 offset:0x1c00
	v_sub_f32_e32 v231, v230, v220
	v_cmp_ge_f32_e32 vcc, s33, v231
	v_max_f32_e32 v231, v220, v220
	v_max_f32_e32 v231, v231, v230
	v_sub_f32_e32 v230, v220, v231
	v_mul_f32_e32 v230, 0x3e0293ee, v230
	v_exp_f32_e32 v230, v230
	v_mfma_f32_32x32x16_bf16 v[48:63], v[170:173], v[200:203], v[48:63]
	ds_read_b64_tr_b16 v[200:201], v191 offset:0x2400
	ds_read_b64_tr_b16 v[202:203], v191 offset:0x2c00
	s_cmp_eq_u64 vcc, exec
	s_cselect_b64 s[8:9], -1, 0
	v_cndmask_b32_e64 v241, v230, 1.0, s[8:9]
	v_cndmask_b32_e64 v232, v231, v220, s[8:9]
	v_mul_f32_e32 v240, 0xbe0293ee, v232
	v_mfma_f32_32x32x16_bf16 v[48:63], v[174:177], v[224:227], v[48:63]
	ds_read_b64_tr_b16 v[224:225], v191 offset:0x3400
	ds_read_b64_tr_b16 v[226:227], v191 offset:0x3c00
	v_fmamk_f32 v80, v80, 0x3e0293ee, v240
	v_fmamk_f32 v81, v81, 0x3e0293ee, v240
	v_fmamk_f32 v82, v82, 0x3e0293ee, v240
	s_waitcnt lgkmcnt(0)
	v_mfma_f32_32x32x16_bf16 v[32:47], v[162:165], v[184:187], v[32:47]
	ds_read_b64_tr_b16 v[184:185], v191 offset:0x600
	ds_read_b64_tr_b16 v[186:187], v191 offset:0xe00
	v_fmamk_f32 v83, v83, 0x3e0293ee, v240
	v_fmamk_f32 v84, v84, 0x3e0293ee, v240
	v_fmamk_f32 v85, v85, 0x3e0293ee, v240
	v_fmamk_f32 v86, v86, 0x3e0293ee, v240
	v_mfma_f32_32x32x16_bf16 v[32:47], v[166:169], v[196:199], v[32:47]
	ds_read_b64_tr_b16 v[196:197], v191 offset:0x1600
	ds_read_b64_tr_b16 v[198:199], v191 offset:0x1e00
	v_fmamk_f32 v87, v87, 0x3e0293ee, v240
	v_fmamk_f32 v88, v88, 0x3e0293ee, v240
	v_fmamk_f32 v89, v89, 0x3e0293ee, v240
	v_fmamk_f32 v90, v90, 0x3e0293ee, v240
	v_mfma_f32_32x32x16_bf16 v[32:47], v[170:173], v[200:203], v[32:47]
	ds_read_b64_tr_b16 v[200:201], v191 offset:0x2600
	ds_read_b64_tr_b16 v[202:203], v191 offset:0x2e00
	v_fmamk_f32 v91, v91, 0x3e0293ee, v240
	v_fmamk_f32 v92, v92, 0x3e0293ee, v240
	v_fmamk_f32 v93, v93, 0x3e0293ee, v240
	v_mfma_f32_32x32x16_bf16 v[32:47], v[174:177], v[224:227], v[32:47]
	ds_read_b64_tr_b16 v[224:225], v191 offset:0x3600
	ds_read_b64_tr_b16 v[226:227], v191 offset:0x3e00
	v_fmamk_f32 v94, v94, 0x3e0293ee, v240
	v_fmamk_f32 v95, v95, 0x3e0293ee, v240
	s_waitcnt lgkmcnt(0)
	v_mfma_f32_32x32x16_bf16 v[16:31], v[162:165], v[184:187], v[16:31]
	v_exp_f32_e32 v163, v80
	v_exp_f32_e32 v164, v82
	v_exp_f32_e32 v165, v86
	v_exp_f32_e32 v184, v83
	v_exp_f32_e32 v185, v85
	v_mfma_f32_32x32x16_bf16 v[16:31], v[166:169], v[196:199], v[16:31]
	v_exp_f32_e32 v166, v88
	v_exp_f32_e32 v167, v90
	v_exp_f32_e32 v168, v92
	v_exp_f32_e32 v169, v94
	v_mfma_f32_32x32x16_bf16 v[16:31], v[170:173], v[200:203], v[16:31]
	v_exp_f32_e32 v171, v93
	v_exp_f32_e32 v172, v95
	v_exp_f32_e32 v173, v89
	v_mfma_f32_32x32x16_bf16 v[16:31], v[174:177], v[224:227], v[16:31]
	v_exp_f32_e32 v177, v81
	v_exp_f32_e32 v176, v84
	v_exp_f32_e32 v175, v87
	v_exp_f32_e32 v174, v91
	s_barrier
	s_waitcnt vmcnt(4)
	v_mov_b32_e32 v162, v241
	v_cmp_gt_f32_e32 vcc, 1.0, v162
	s_waitcnt vmcnt(3)
	ds_write_b128 v205, v[146:149] offset:16384
	s_waitcnt vmcnt(2)
	ds_write_b128 v206, v[150:153] offset:16384
	s_waitcnt vmcnt(1)
	ds_write_b128 v204, v[154:157] offset:49152
	s_waitcnt vmcnt(0)
	ds_write_b128 v207, v[158:161] offset:49152
	s_cbranch_vccz .LBB0_545
	s_and_saveexec_b64 s[12:13], s[6:7]
	ds_write_b32 v190, v162 offset:128
	s_or_b64 exec, exec, s[12:13]
	s_waitcnt lgkmcnt(0)
	ds_read_b128 v[146:149], v179 offset:224
	ds_read_b128 v[150:153], v179 offset:192
	ds_read_b128 v[154:157], v179 offset:160
	ds_read_b128 v[158:161], v179 offset:128
	s_waitcnt lgkmcnt(3)
	v_pk_mul_f32 v[14:15], v[14:15], v[148:149]
	s_waitcnt lgkmcnt(2)
	v_pk_mul_f32 v[10:11], v[10:11], v[152:153]
	s_waitcnt lgkmcnt(1)
	v_pk_mul_f32 v[6:7], v[6:7], v[156:157]
	s_waitcnt lgkmcnt(0)
	v_pk_mul_f32 v[2:3], v[2:3], v[160:161]
	v_pk_mul_f32 v[12:13], v[12:13], v[146:147]
	v_pk_mul_f32 v[8:9], v[8:9], v[150:151]
	v_pk_mul_f32 v[4:5], v[4:5], v[154:155]
	v_pk_mul_f32 v[0:1], v[0:1], v[158:159]
	v_pk_mul_f32 v[62:63], v[62:63], v[148:149]
	v_pk_mul_f32 v[58:59], v[58:59], v[152:153]
	v_pk_mul_f32 v[54:55], v[54:55], v[156:157]
	v_pk_mul_f32 v[50:51], v[50:51], v[160:161]
	v_pk_mul_f32 v[60:61], v[60:61], v[146:147]
	v_pk_mul_f32 v[56:57], v[56:57], v[150:151]
	v_pk_mul_f32 v[52:53], v[52:53], v[154:155]
	v_pk_mul_f32 v[48:49], v[48:49], v[158:159]
	v_pk_mul_f32 v[46:47], v[46:47], v[148:149]
	v_pk_mul_f32 v[42:43], v[42:43], v[152:153]
	v_pk_mul_f32 v[38:39], v[38:39], v[156:157]
	v_pk_mul_f32 v[34:35], v[34:35], v[160:161]
	v_pk_mul_f32 v[44:45], v[44:45], v[146:147]
	v_pk_mul_f32 v[40:41], v[40:41], v[150:151]
	v_pk_mul_f32 v[36:37], v[36:37], v[154:155]
	v_pk_mul_f32 v[32:33], v[32:33], v[158:159]
	v_pk_mul_f32 v[30:31], v[30:31], v[148:149]
	v_pk_mul_f32 v[26:27], v[26:27], v[152:153]
	v_pk_mul_f32 v[22:23], v[22:23], v[156:157]
	v_pk_mul_f32 v[18:19], v[18:19], v[160:161]
	v_pk_mul_f32 v[28:29], v[28:29], v[146:147]
	v_pk_mul_f32 v[24:25], v[24:25], v[150:151]
	v_pk_mul_f32 v[20:21], v[20:21], v[154:155]
	v_pk_mul_f32 v[16:17], v[16:17], v[158:159]
.LBB0_545:
	v_mov_b32_e32 v170, v232
	v_mul_f32_e32 v146, 0xbe0293ee, v170
	v_mov_b32_e32 v147, v146
	v_pk_fma_f32 v[160:161], v[64:65], s[76:77], v[146:147] op_sel_hi:[1,0,0]
	v_add_f32_e32 v64, v217, v218
	v_fmac_f32_e32 v64, v216, v192
	v_add_f32_e32 v192, v221, v222
	v_pk_fma_f32 v[158:159], v[66:67], s[76:77], v[146:147] op_sel_hi:[1,0,0]
	v_pk_fma_f32 v[154:155], v[68:69], s[76:77], v[146:147] op_sel_hi:[1,0,0]
	v_pk_fma_f32 v[150:151], v[70:71], s[76:77], v[146:147] op_sel_hi:[1,0,0]
	v_pk_fma_f32 v[148:149], v[72:73], s[76:77], v[146:147] op_sel_hi:[1,0,0]
	v_pk_fma_f32 v[156:157], v[74:75], s[76:77], v[146:147] op_sel_hi:[1,0,0]
	v_pk_fma_f32 v[152:153], v[76:77], s[76:77], v[146:147] op_sel_hi:[1,0,0]
	v_pk_fma_f32 v[146:147], v[78:79], s[76:77], v[146:147] op_sel_hi:[1,0,0]
	v_fmac_f32_e32 v192, v64, v219
	v_lshl_add_u64 v[180:181], v[180:181], 0, s[78:79]
	v_lshl_add_u64 v[182:183], v[182:183], 0, s[78:79]
	s_add_i32 s30, s30, 2
	s_and_b64 vcc, exec, s[10:11]
	s_waitcnt lgkmcnt(0)
	s_barrier
	s_cbranch_vccnz .LBB0_547
	v_mov_b32_e32 v216, v162
	s_branch .LBB0_535
